# v43 (keep10) + attention unit queue takes its ticket directly from the own-XCD queue (coherent pre-check load in front of the atomic removed)
# speedup vs baseline: 1.0083x; 1.0083x over previous
.LBB0_476:
	s_waitcnt vmcnt(0)
	s_barrier
	s_and_saveexec_b64 s[4:5], s[90:91]
	s_cbranch_execz .LBB0_537
	v_mov_b32_e32 v0, 0
	s_mov_b64 s[42:43], exec
	v_mbcnt_lo_u32_b32 v0, s42, 0
	v_mbcnt_hi_u32_b32 v0, s43, v0
	v_cmp_eq_u32_e32 vcc, 0, v0
	s_and_saveexec_b64 s[6:7], vcc
	s_cbranch_execz .LBB0_480
	s_bcnt1_i32_b64 s42, s[42:43]
	v_mov_b32_e32 v2, s42
	global_atomic_add v2, v1, v2, s[10:11] offset:1632 sc0

.LBB0_1531:
	s_barrier
	s_and_saveexec_b64 s[4:5], s[90:91]
	s_cbranch_execz .LBB0_1592
	v_mov_b32_e32 v0, 0
	s_mov_b64 s[42:43], exec
	v_mbcnt_lo_u32_b32 v0, s42, 0
	v_mbcnt_hi_u32_b32 v0, s43, v0
	v_cmp_eq_u32_e32 vcc, 0, v0
	s_and_saveexec_b64 s[6:7], vcc
	s_cbranch_execz .LBB0_1535
	s_bcnt1_i32_b64 s42, s[42:43]
	v_mov_b32_e32 v2, s42
	global_atomic_add v2, v1, v2, s[10:11] offset:1888 sc0
